# k12
# baseline (speedup 1.0000x reference)
; __device__ __forceinline__ void mirror_phase(u16* __restrict__ F, const float* __restrict__ alt, const float* __restrict__ E, unsigned sx, unsigned srank, unsigned snloc) {
;     ...
;   for (int li = (int)srank * NTHREADS + tid; li < DM; li += (int)snloc * NTHREADS) {
;     const int idx = (int)sx * DM + li;
;     float s = E[idx];
; #pragma unroll 8
;     for (int q = 0; q < 64; ++q) s += alt[(size_t)q * (NBATCH * DM) + idx];
;     const int b = idx >> 10, n = idx & 1023;
;     F[((size_t)b * SEQ + 2048) * DM + n] = f2bf(s * (1.0f / 1024.0f));
;   }
.LBB0_510:
	s_mov_b32 s3, 0
	s_mov_b32 s2, 0x4000000
	v_lshl_add_u64 v[8:9], v[0:1], 0, s[2:3]
	global_load_dword v20, v[8:9], off
	s_mov_b32 s2, 0x4008000
	v_lshl_add_u64 v[8:9], v[0:1], 0, s[2:3]
	global_load_dword v21, v[8:9], off
	s_mov_b32 s2, 0x4010000
	v_lshl_add_u64 v[8:9], v[0:1], 0, s[2:3]
	global_load_dword v22, v[8:9], off
	s_mov_b32 s2, 0x4018000
	v_lshl_add_u64 v[8:9], v[0:1], 0, s[2:3]
	global_load_dword v23, v[8:9], off
	s_mov_b32 s2, 0x4020000
	v_lshl_add_u64 v[8:9], v[0:1], 0, s[2:3]
	global_load_dword v24, v[8:9], off
	s_mov_b32 s2, 0x4028000
	v_lshl_add_u64 v[8:9], v[0:1], 0, s[2:3]
	global_load_dword v25, v[8:9], off
	s_mov_b32 s2, 0x4030000
	v_lshl_add_u64 v[8:9], v[0:1], 0, s[2:3]
	global_load_dword v26, v[8:9], off
	s_mov_b32 s2, 0x4038000
	v_lshl_add_u64 v[8:9], v[0:1], 0, s[2:3]
	global_load_dword v27, v[8:9], off
	s_mov_b32 s2, 0x4040000
	v_lshl_add_u64 v[8:9], v[0:1], 0, s[2:3]
	global_load_dword v28, v[8:9], off
	s_mov_b32 s2, 0x4048000
	v_lshl_add_u64 v[8:9], v[0:1], 0, s[2:3]
	global_load_dword v29, v[8:9], off
	s_mov_b32 s2, 0x4050000
	v_lshl_add_u64 v[8:9], v[0:1], 0, s[2:3]
	global_load_dword v30, v[8:9], off
	s_mov_b32 s2, 0x4058000
	v_lshl_add_u64 v[8:9], v[0:1], 0, s[2:3]
	global_load_dword v31, v[8:9], off
	s_mov_b32 s2, 0x4060000
	v_lshl_add_u64 v[8:9], v[0:1], 0, s[2:3]
	global_load_dword v32, v[8:9], off
	s_mov_b32 s2, 0x4068000
	v_lshl_add_u64 v[8:9], v[0:1], 0, s[2:3]
	global_load_dword v33, v[8:9], off
	s_mov_b32 s2, 0x4070000
	v_lshl_add_u64 v[8:9], v[0:1], 0, s[2:3]
	global_load_dword v34, v[8:9], off
	s_mov_b32 s2, 0x4078000
	v_lshl_add_u64 v[8:9], v[0:1], 0, s[2:3]
	global_load_dword v35, v[8:9], off
	s_mov_b32 s2, 0x4080000
	v_lshl_add_u64 v[8:9], v[0:1], 0, s[2:3]
	global_load_dword v36, v[8:9], off
	s_mov_b32 s2, 0x4088000
	v_lshl_add_u64 v[8:9], v[0:1], 0, s[2:3]
	global_load_dword v37, v[8:9], off
	s_mov_b32 s2, 0x4090000
	v_lshl_add_u64 v[8:9], v[0:1], 0, s[2:3]
	global_load_dword v38, v[8:9], off
	s_mov_b32 s2, 0x4098000
	v_lshl_add_u64 v[8:9], v[0:1], 0, s[2:3]
	global_load_dword v39, v[8:9], off
	s_mov_b32 s2, 0x40a0000
	v_lshl_add_u64 v[8:9], v[0:1], 0, s[2:3]
	global_load_dword v40, v[8:9], off
	s_mov_b32 s2, 0x40a8000
	v_lshl_add_u64 v[8:9], v[0:1], 0, s[2:3]
	global_load_dword v41, v[8:9], off
	s_mov_b32 s2, 0x40b0000
	v_lshl_add_u64 v[8:9], v[0:1], 0, s[2:3]
	global_load_dword v42, v[8:9], off
	s_mov_b32 s2, 0x40b8000
	v_lshl_add_u64 v[8:9], v[0:1], 0, s[2:3]
	global_load_dword v43, v[8:9], off
	s_mov_b32 s2, 0x40c0000
	v_lshl_add_u64 v[8:9], v[0:1], 0, s[2:3]
	global_load_dword v44, v[8:9], off
	s_mov_b32 s2, 0x40c8000
	v_lshl_add_u64 v[8:9], v[0:1], 0, s[2:3]
	global_load_dword v45, v[8:9], off
	s_mov_b32 s2, 0x40d0000
	v_lshl_add_u64 v[8:9], v[0:1], 0, s[2:3]
	global_load_dword v46, v[8:9], off
	s_mov_b32 s2, 0x40d8000
	v_lshl_add_u64 v[8:9], v[0:1], 0, s[2:3]
	global_load_dword v47, v[8:9], off
	s_mov_b32 s2, 0x40e0000
	v_lshl_add_u64 v[8:9], v[0:1], 0, s[2:3]
	global_load_dword v48, v[8:9], off
	s_mov_b32 s2, 0x40e8000
	v_lshl_add_u64 v[8:9], v[0:1], 0, s[2:3]
	global_load_dword v49, v[8:9], off
	s_mov_b32 s2, 0x40f0000
	v_lshl_add_u64 v[8:9], v[0:1], 0, s[2:3]
	global_load_dword v50, v[8:9], off
	s_mov_b32 s2, 0x40f8000
	v_lshl_add_u64 v[8:9], v[0:1], 0, s[2:3]
	global_load_dword v51, v[8:9], off
	s_mov_b32 s2, 0x4100000
	v_lshl_add_u64 v[8:9], v[0:1], 0, s[2:3]
	global_load_dword v52, v[8:9], off
	s_mov_b32 s2, 0x4108000
	v_lshl_add_u64 v[8:9], v[0:1], 0, s[2:3]
	global_load_dword v53, v[8:9], off
	s_mov_b32 s2, 0x4110000
	v_lshl_add_u64 v[8:9], v[0:1], 0, s[2:3]
	global_load_dword v54, v[8:9], off
	s_mov_b32 s2, 0x4118000
	v_lshl_add_u64 v[8:9], v[0:1], 0, s[2:3]
	global_load_dword v55, v[8:9], off
	s_mov_b32 s2, 0x4120000
	v_lshl_add_u64 v[8:9], v[0:1], 0, s[2:3]
	global_load_dword v56, v[8:9], off
	s_mov_b32 s2, 0x4128000
	v_lshl_add_u64 v[8:9], v[0:1], 0, s[2:3]
	global_load_dword v57, v[8:9], off
	s_mov_b32 s2, 0x4130000
	v_lshl_add_u64 v[8:9], v[0:1], 0, s[2:3]
	global_load_dword v58, v[8:9], off
	s_mov_b32 s2, 0x4138000
	v_lshl_add_u64 v[8:9], v[0:1], 0, s[2:3]
	global_load_dword v59, v[8:9], off
	s_mov_b32 s2, 0x4140000
	v_lshl_add_u64 v[8:9], v[0:1], 0, s[2:3]
	global_load_dword v60, v[8:9], off
	s_mov_b32 s2, 0x4148000
	v_lshl_add_u64 v[8:9], v[0:1], 0, s[2:3]
	global_load_dword v61, v[8:9], off
	s_mov_b32 s2, 0x4150000
	v_lshl_add_u64 v[8:9], v[0:1], 0, s[2:3]
	global_load_dword v62, v[8:9], off
	s_mov_b32 s2, 0x4158000
	v_lshl_add_u64 v[8:9], v[0:1], 0, s[2:3]
	global_load_dword v63, v[8:9], off
	s_mov_b32 s2, 0x4160000
	v_lshl_add_u64 v[8:9], v[0:1], 0, s[2:3]
	global_load_dword v64, v[8:9], off
	s_mov_b32 s2, 0x4168000
	v_lshl_add_u64 v[8:9], v[0:1], 0, s[2:3]
	global_load_dword v65, v[8:9], off
	s_mov_b32 s2, 0x4170000
	v_lshl_add_u64 v[8:9], v[0:1], 0, s[2:3]
	global_load_dword v66, v[8:9], off
	s_mov_b32 s2, 0x4178000
	v_lshl_add_u64 v[8:9], v[0:1], 0, s[2:3]
	global_load_dword v67, v[8:9], off
	s_mov_b32 s2, 0x4180000
	v_lshl_add_u64 v[8:9], v[0:1], 0, s[2:3]
	global_load_dword v68, v[8:9], off
	s_mov_b32 s2, 0x4188000
	v_lshl_add_u64 v[8:9], v[0:1], 0, s[2:3]
	global_load_dword v69, v[8:9], off
	s_mov_b32 s2, 0x4190000
	v_lshl_add_u64 v[8:9], v[0:1], 0, s[2:3]
	global_load_dword v70, v[8:9], off
	s_mov_b32 s2, 0x4198000
	v_lshl_add_u64 v[8:9], v[0:1], 0, s[2:3]
	global_load_dword v71, v[8:9], off
	s_mov_b32 s2, 0x41a0000
	v_lshl_add_u64 v[8:9], v[0:1], 0, s[2:3]
	global_load_dword v72, v[8:9], off
	s_mov_b32 s2, 0x41a8000
	v_lshl_add_u64 v[8:9], v[0:1], 0, s[2:3]
	global_load_dword v73, v[8:9], off
	s_mov_b32 s2, 0x41b0000
	v_lshl_add_u64 v[8:9], v[0:1], 0, s[2:3]
	global_load_dword v74, v[8:9], off
	s_mov_b32 s2, 0x41b8000
	v_lshl_add_u64 v[8:9], v[0:1], 0, s[2:3]
	global_load_dword v75, v[8:9], off
	s_mov_b32 s2, 0x41c0000
	v_lshl_add_u64 v[8:9], v[0:1], 0, s[2:3]
	global_load_dword v76, v[8:9], off
	s_mov_b32 s2, 0x41c8000
	v_lshl_add_u64 v[8:9], v[0:1], 0, s[2:3]
	global_load_dword v77, v[8:9], off
	s_mov_b32 s2, 0x41d0000
	v_lshl_add_u64 v[8:9], v[0:1], 0, s[2:3]
	global_load_dword v78, v[8:9], off
	s_mov_b32 s2, 0x41d8000
	v_lshl_add_u64 v[8:9], v[0:1], 0, s[2:3]
	global_load_dword v79, v[8:9], off
	s_mov_b32 s2, 0x41e0000
	v_lshl_add_u64 v[8:9], v[0:1], 0, s[2:3]
	global_load_dword v80, v[8:9], off
	s_mov_b32 s2, 0x41e8000
	v_lshl_add_u64 v[8:9], v[0:1], 0, s[2:3]
	global_load_dword v81, v[8:9], off
	s_mov_b32 s2, 0x41f0000
	v_lshl_add_u64 v[8:9], v[0:1], 0, s[2:3]
	global_load_dword v82, v[8:9], off
	s_mov_b32 s2, 0x41f8000
	v_lshl_add_u64 v[8:9], v[0:1], 0, s[2:3]
	global_load_dword v83, v[8:9], off
	s_waitcnt vmcnt(63)
; __device__ __forceinline__ void mirror_phase(u16* __restrict__ F, const float* __restrict__ alt, const float* __restrict__ E, unsigned sx, unsigned srank, unsigned snloc) {
;     ...
;   for (int li = (int)srank * NTHREADS + tid; li < DM; li += (int)snloc * NTHREADS) {
;     const int idx = (int)sx * DM + li;
;     float s = E[idx];
; #pragma unroll 8
;     for (int q = 0; q < 64; ++q) s += alt[(size_t)q * (NBATCH * DM) + idx];
;     const int b = idx >> 10, n = idx & 1023;
;     F[((size_t)b * SEQ + 2048) * DM + n] = f2bf(s * (1.0f / 1024.0f));
;   }
	v_add_f32_e32 v3, v3, v20
	s_waitcnt vmcnt(62)
	v_add_f32_e32 v3, v3, v21
	s_waitcnt vmcnt(61)
	v_add_f32_e32 v3, v3, v22
	s_waitcnt vmcnt(60)
	v_add_f32_e32 v3, v3, v23
	s_waitcnt vmcnt(59)
	v_add_f32_e32 v3, v3, v24
	s_waitcnt vmcnt(58)
	v_add_f32_e32 v3, v3, v25
	s_waitcnt vmcnt(57)
	v_add_f32_e32 v3, v3, v26
	s_waitcnt vmcnt(56)
	v_add_f32_e32 v3, v3, v27
	s_waitcnt vmcnt(55)
	v_add_f32_e32 v3, v3, v28
	s_waitcnt vmcnt(54)
	v_add_f32_e32 v3, v3, v29
	s_waitcnt vmcnt(53)
	v_add_f32_e32 v3, v3, v30
	s_waitcnt vmcnt(52)
	v_add_f32_e32 v3, v3, v31
	s_waitcnt vmcnt(51)
	v_add_f32_e32 v3, v3, v32
	s_waitcnt vmcnt(50)
	v_add_f32_e32 v3, v3, v33
	s_waitcnt vmcnt(49)
	v_add_f32_e32 v3, v3, v34
	s_waitcnt vmcnt(48)
	v_add_f32_e32 v3, v3, v35
	s_waitcnt vmcnt(47)
	v_add_f32_e32 v3, v3, v36
	s_waitcnt vmcnt(46)
	v_add_f32_e32 v3, v3, v37
	s_waitcnt vmcnt(45)
	v_add_f32_e32 v3, v3, v38
	s_waitcnt vmcnt(44)
	v_add_f32_e32 v3, v3, v39
	s_waitcnt vmcnt(43)
	v_add_f32_e32 v3, v3, v40
	s_waitcnt vmcnt(42)
	v_add_f32_e32 v3, v3, v41
	s_waitcnt vmcnt(41)
	v_add_f32_e32 v3, v3, v42
	s_waitcnt vmcnt(40)
	v_add_f32_e32 v3, v3, v43
	s_waitcnt vmcnt(39)
	v_add_f32_e32 v3, v3, v44
	s_waitcnt vmcnt(38)
	v_add_f32_e32 v3, v3, v45
	s_waitcnt vmcnt(37)
	v_add_f32_e32 v3, v3, v46
	s_waitcnt vmcnt(36)
	v_add_f32_e32 v3, v3, v47
	s_waitcnt vmcnt(35)
	v_add_f32_e32 v3, v3, v48
	s_waitcnt vmcnt(34)
	v_add_f32_e32 v3, v3, v49
	s_waitcnt vmcnt(33)
	v_add_f32_e32 v3, v3, v50
	s_waitcnt vmcnt(32)
	v_add_f32_e32 v3, v3, v51
	s_waitcnt vmcnt(31)
	v_add_f32_e32 v3, v3, v52
	s_waitcnt vmcnt(30)
	v_add_f32_e32 v3, v3, v53
	s_waitcnt vmcnt(29)
	v_add_f32_e32 v3, v3, v54
	s_waitcnt vmcnt(28)
	v_add_f32_e32 v3, v3, v55
	s_waitcnt vmcnt(27)
	v_add_f32_e32 v3, v3, v56
	s_waitcnt vmcnt(26)
	v_add_f32_e32 v3, v3, v57
	s_waitcnt vmcnt(25)
	v_add_f32_e32 v3, v3, v58
	s_waitcnt vmcnt(24)
	v_add_f32_e32 v3, v3, v59
	s_waitcnt vmcnt(23)
	v_add_f32_e32 v3, v3, v60
	s_waitcnt vmcnt(22)
	v_add_f32_e32 v3, v3, v61
	s_waitcnt vmcnt(21)
	v_add_f32_e32 v3, v3, v62
	s_waitcnt vmcnt(20)
	v_add_f32_e32 v3, v3, v63
	s_waitcnt vmcnt(19)
	v_add_f32_e32 v3, v3, v64
	s_waitcnt vmcnt(18)
	v_add_f32_e32 v3, v3, v65
	s_waitcnt vmcnt(17)
	v_add_f32_e32 v3, v3, v66
	s_waitcnt vmcnt(16)
	v_add_f32_e32 v3, v3, v67
	s_waitcnt vmcnt(15)
	v_add_f32_e32 v3, v3, v68
	s_waitcnt vmcnt(14)
	v_add_f32_e32 v3, v3, v69
	s_waitcnt vmcnt(13)
	v_add_f32_e32 v3, v3, v70
	s_waitcnt vmcnt(12)
	v_add_f32_e32 v3, v3, v71
	s_waitcnt vmcnt(11)
	v_add_f32_e32 v3, v3, v72
	s_waitcnt vmcnt(10)
	v_add_f32_e32 v3, v3, v73
	s_waitcnt vmcnt(9)
	v_add_f32_e32 v3, v3, v74
	s_waitcnt vmcnt(8)
	v_add_f32_e32 v3, v3, v75
	s_waitcnt vmcnt(7)
	v_add_f32_e32 v3, v3, v76
	s_waitcnt vmcnt(6)
	v_add_f32_e32 v3, v3, v77
	s_waitcnt vmcnt(5)
	v_add_f32_e32 v3, v3, v78
	s_waitcnt vmcnt(4)
	v_add_f32_e32 v3, v3, v79
	s_waitcnt vmcnt(3)
	v_add_f32_e32 v3, v3, v80
	s_waitcnt vmcnt(2)
	v_add_f32_e32 v3, v3, v81
	s_waitcnt vmcnt(1)
	v_add_f32_e32 v3, v3, v82
	s_waitcnt vmcnt(0)
	v_add_f32_e32 v3, v3, v83
	v_mul_f32_e32 v3, 0x3a800000, v3
	v_ashrrev_i32_e32 v2, 10, v2
	v_bfe_u32 v6, v3, 16, 1
	v_add3_u32 v6, v3, v6, s74
	v_ashrrev_i32_e32 v3, 31, v2
	v_and_b32_e32 v5, 0x3ff, v4
	v_lshlrev_b64 v[2:3], 23, v[2:3]
	v_lshl_add_u64 v[2:3], s[6:7], 0, v[2:3]
	v_lshlrev_b32_e32 v176, 1, v5
	v_lshl_add_u64 v[2:3], v[2:3], 0, v[176:177]
	v_readlane_b32 s2, v238, 50
	v_add_co_u32_e32 v2, vcc, 0x400000, v2
	v_readlane_b32 s3, v238, 51
	s_nop 0
	v_addc_co_u32_e32 v3, vcc, 0, v3, vcc
	v_add_u32_e32 v4, s2, v4
	s_movk_i32 s0, 0x3ff
	v_readlane_b32 s2, v238, 52
	v_cmp_lt_i32_e32 vcc, s0, v4
	v_readlane_b32 s3, v238, 53
	s_or_b64 s[10:11], vcc, s[10:11]
	global_store_short_d16_hi v[2:3], v6, off
	v_lshl_add_u64 v[0:1], v[0:1], 0, s[2:3]
	s_andn2_b64 exec, exec, s[10:11]
	s_cbranch_execnz .LBB0_509
